# GEMM K-loops (P1/P5/P7): LDS-DMA loads use SGPR base + 32-bit lane offset instead of per-load 64-bit VALU address adds (48 v_lshl_add_u64 removed)
# baseline (speedup 1.0000x reference)
.LBB0_187:
	ds_read_b128 v[154:157], v150
	ds_read_b128 v[158:161], v150 offset:1024
	ds_read_b128 v[162:165], v150 offset:2048
	ds_read_b128 v[166:169], v150 offset:3072
	s_add_u32 s20, s18, 0xfff80080
	s_addc_u32 s21, s19, -1
	s_cmp_eq_u32 s52, 28
	s_cselect_b32 s23, s11, s21
	s_cselect_b32 s22, s44, s20
	s_cselect_b32 s21, s9, s51
	s_cselect_b32 s20, s45, s50
	s_add_i32 m0, s17, 0xc000
	ds_read_b128 v[170:173], v151
	ds_read_b128 v[174:177], v151 offset:1024
	ds_read_b128 v[178:181], v151 offset:2048
	ds_read_b128 v[182:185], v151 offset:3072
	ds_read_b128 v[186:189], v151 offset:4096
	ds_read_b128 v[190:193], v151 offset:5120
	ds_read_b128 v[194:197], v151 offset:6144
	ds_read_b128 v[198:201], v151 offset:7168
	global_load_lds_dwordx4 v138, s[18:19]
	s_add_i32 m0, s17, 0xe000
	s_nop 0
	global_load_lds_dwordx4 v140, s[18:19]
	s_waitcnt lgkmcnt(8)
	s_barrier
	s_waitcnt lgkmcnt(0)
	s_setprio 1
	s_waitcnt lgkmcnt(0)
	v_mfma_f32_16x16x32_bf16 v[124:127], v[154:157], v[170:173], v[124:127]
	v_mfma_f32_16x16x32_bf16 v[120:123], v[162:165], v[170:173], v[120:123]
	v_mfma_f32_16x16x32_bf16 v[112:115], v[154:157], v[178:181], v[112:115]
	v_mfma_f32_16x16x32_bf16 v[104:107], v[162:165], v[178:181], v[104:107]
	v_mfma_f32_16x16x32_bf16 v[96:99], v[154:157], v[186:189], v[96:99]
	v_mfma_f32_16x16x32_bf16 v[88:91], v[162:165], v[186:189], v[88:91]
	v_mfma_f32_16x16x32_bf16 v[80:83], v[154:157], v[194:197], v[80:83]
	v_mfma_f32_16x16x32_bf16 v[72:75], v[162:165], v[194:197], v[72:75]
	v_mfma_f32_16x16x32_bf16 v[124:127], v[158:161], v[174:177], v[124:127]
	v_mfma_f32_16x16x32_bf16 v[120:123], v[166:169], v[174:177], v[120:123]
	v_mfma_f32_16x16x32_bf16 v[112:115], v[158:161], v[182:185], v[112:115]
	v_mfma_f32_16x16x32_bf16 v[104:107], v[166:169], v[182:185], v[104:107]
	v_mfma_f32_16x16x32_bf16 v[96:99], v[158:161], v[190:193], v[96:99]
	v_mfma_f32_16x16x32_bf16 v[88:91], v[166:169], v[190:193], v[88:91]
	v_mfma_f32_16x16x32_bf16 v[80:83], v[158:161], v[198:201], v[80:83]
	v_mfma_f32_16x16x32_bf16 v[72:75], v[166:169], v[198:201], v[72:75]
	s_setprio 0
	s_barrier
	s_add_i32 s53, s40, s27
	s_add_u32 s98, s20, s6
	s_addc_u32 s99, s21, s7
	s_mov_b32 m0, s53
	ds_read_b128 v[202:205], v152
	ds_read_b128 v[206:209], v152 offset:1024
	ds_read_b128 v[210:213], v152 offset:2048
	ds_read_b128 v[214:217], v152 offset:3072
	global_load_lds_dwordx4 v132, s[20:21]
	s_add_i32 m0, s53, 0x2000
	s_nop 0
	global_load_lds_dwordx4 v136, s[20:21]
	s_barrier
	s_waitcnt lgkmcnt(0)
	s_setprio 1
	s_waitcnt lgkmcnt(0)
	v_mfma_f32_16x16x32_bf16 v[116:119], v[202:205], v[170:173], v[116:119]
	v_mfma_f32_16x16x32_bf16 v[108:111], v[210:213], v[170:173], v[108:111]
	v_mfma_f32_16x16x32_bf16 v[100:103], v[202:205], v[178:181], v[100:103]
	v_mfma_f32_16x16x32_bf16 v[92:95], v[210:213], v[178:181], v[92:95]
	v_mfma_f32_16x16x32_bf16 v[84:87], v[202:205], v[186:189], v[84:87]
	v_mfma_f32_16x16x32_bf16 v[76:79], v[210:213], v[186:189], v[76:79]
	v_mfma_f32_16x16x32_bf16 v[68:71], v[202:205], v[194:197], v[68:71]
	v_mfma_f32_16x16x32_bf16 v[64:67], v[210:213], v[194:197], v[64:67]
	v_mfma_f32_16x16x32_bf16 v[116:119], v[206:209], v[174:177], v[116:119]
	v_mfma_f32_16x16x32_bf16 v[108:111], v[214:217], v[174:177], v[108:111]
	v_mfma_f32_16x16x32_bf16 v[100:103], v[206:209], v[182:185], v[100:103]
	v_mfma_f32_16x16x32_bf16 v[92:95], v[214:217], v[182:185], v[92:95]
	v_mfma_f32_16x16x32_bf16 v[84:87], v[206:209], v[190:193], v[84:87]
	v_mfma_f32_16x16x32_bf16 v[76:79], v[214:217], v[190:193], v[76:79]
	v_mfma_f32_16x16x32_bf16 v[68:71], v[206:209], v[198:201], v[68:71]
	v_mfma_f32_16x16x32_bf16 v[64:67], v[214:217], v[198:201], v[64:67]
	s_setprio 0
	s_mov_b32 m0, s17
	s_add_u32 s100, s22, s6
	s_addc_u32 s101, s23, s7
	s_barrier
	ds_read_b128 v[170:173], v151 offset:16384
	ds_read_b128 v[174:177], v151 offset:17408
	ds_read_b128 v[178:181], v151 offset:18432
	ds_read_b128 v[182:185], v151 offset:19456
	ds_read_b128 v[186:189], v151 offset:20480
	ds_read_b128 v[190:193], v151 offset:21504
	ds_read_b128 v[194:197], v151 offset:22528
	ds_read_b128 v[198:201], v151 offset:23552
	global_load_lds_dwordx4 v130, s[22:23]
	s_mov_b32 m0, s30
	s_nop 0
	global_load_lds_dwordx4 v134, s[22:23]
	s_barrier
	s_waitcnt lgkmcnt(0)
	s_setprio 1
	s_waitcnt lgkmcnt(0)
	v_mfma_f32_16x16x32_bf16 v[60:63], v[154:157], v[170:173], v[60:63]
	v_mfma_f32_16x16x32_bf16 v[56:59], v[162:165], v[170:173], v[56:59]
	v_mfma_f32_16x16x32_bf16 v[48:51], v[154:157], v[178:181], v[48:51]
	v_mfma_f32_16x16x32_bf16 v[40:43], v[162:165], v[178:181], v[40:43]
	v_mfma_f32_16x16x32_bf16 v[32:35], v[154:157], v[186:189], v[32:35]
	v_mfma_f32_16x16x32_bf16 v[24:27], v[162:165], v[186:189], v[24:27]
	v_mfma_f32_16x16x32_bf16 v[16:19], v[154:157], v[194:197], v[16:19]
	v_mfma_f32_16x16x32_bf16 v[8:11], v[162:165], v[194:197], v[8:11]
	v_mfma_f32_16x16x32_bf16 v[60:63], v[158:161], v[174:177], v[60:63]
	v_mfma_f32_16x16x32_bf16 v[56:59], v[166:169], v[174:177], v[56:59]
	v_mfma_f32_16x16x32_bf16 v[48:51], v[158:161], v[182:185], v[48:51]
	v_mfma_f32_16x16x32_bf16 v[40:43], v[166:169], v[182:185], v[40:43]
	v_mfma_f32_16x16x32_bf16 v[32:35], v[158:161], v[190:193], v[32:35]
	v_mfma_f32_16x16x32_bf16 v[24:27], v[166:169], v[190:193], v[24:27]
	v_mfma_f32_16x16x32_bf16 v[16:19], v[158:161], v[198:201], v[16:19]
	v_mfma_f32_16x16x32_bf16 v[8:11], v[166:169], v[198:201], v[8:11]
	s_setprio 0
	s_barrier
	s_add_u32 s54, s20, 0x80000
	s_addc_u32 s55, s21, 0
	s_add_i32 s53, s41, s27
	s_mov_b32 m0, s53
	s_nop 0
	global_load_lds_dwordx4 v132, s[54:55]
	s_add_i32 m0, s53, 0x2000
	s_nop 0
	global_load_lds_dwordx4 v136, s[54:55]
	s_waitcnt vmcnt(6)
	s_barrier
	s_setprio 1
	v_mfma_f32_16x16x32_bf16 v[52:55], v[202:205], v[170:173], v[52:55]
	v_mfma_f32_16x16x32_bf16 v[44:47], v[210:213], v[170:173], v[44:47]
	v_mfma_f32_16x16x32_bf16 v[36:39], v[202:205], v[178:181], v[36:39]
	v_mfma_f32_16x16x32_bf16 v[28:31], v[210:213], v[178:181], v[28:31]
	v_mfma_f32_16x16x32_bf16 v[20:23], v[202:205], v[186:189], v[20:23]
	v_mfma_f32_16x16x32_bf16 v[12:15], v[210:213], v[186:189], v[12:15]
	v_mfma_f32_16x16x32_bf16 v[4:7], v[202:205], v[194:197], v[4:7]
	v_mfma_f32_16x16x32_bf16 v[0:3], v[210:213], v[194:197], v[0:3]
	v_mfma_f32_16x16x32_bf16 v[52:55], v[206:209], v[174:177], v[52:55]
	v_mfma_f32_16x16x32_bf16 v[44:47], v[214:217], v[174:177], v[44:47]
	v_mfma_f32_16x16x32_bf16 v[36:39], v[206:209], v[182:185], v[36:39]
	v_mfma_f32_16x16x32_bf16 v[28:31], v[214:217], v[182:185], v[28:31]
	v_mfma_f32_16x16x32_bf16 v[20:23], v[206:209], v[190:193], v[20:23]
	v_mfma_f32_16x16x32_bf16 v[12:15], v[214:217], v[190:193], v[12:15]
	v_mfma_f32_16x16x32_bf16 v[4:7], v[206:209], v[198:201], v[4:7]
	v_mfma_f32_16x16x32_bf16 v[0:3], v[214:217], v[198:201], v[0:3]
	s_setprio 0
	s_add_i32 s53, 16, 0x18000
	v_add_u32_e32 v153, s53, v148
	s_barrier
	ds_read_b128 v[154:157], v153
	ds_read_b128 v[158:161], v153 offset:1024
	ds_read_b128 v[162:165], v153 offset:2048
	ds_read_b128 v[166:169], v153 offset:3072
	s_add_u32 s22, s22, 0x80000
	s_addc_u32 s23, s23, 0
	s_mov_b32 m0, s31
	ds_read_b128 v[170:173], v151 offset:32768
	ds_read_b128 v[174:177], v151 offset:33792
	ds_read_b128 v[178:181], v151 offset:34816
	ds_read_b128 v[182:185], v151 offset:35840
	ds_read_b128 v[186:189], v151 offset:36864
	ds_read_b128 v[190:193], v151 offset:37888
	ds_read_b128 v[194:197], v151 offset:38912
	ds_read_b128 v[198:201], v151 offset:39936
	global_load_lds_dwordx4 v130, s[22:23]
	s_mov_b32 m0, s34
	s_nop 0
	global_load_lds_dwordx4 v134, s[22:23]
	s_waitcnt lgkmcnt(8)
	s_barrier
	s_waitcnt lgkmcnt(0)
	s_setprio 1
	s_waitcnt lgkmcnt(0)
	v_mfma_f32_16x16x32_bf16 v[124:127], v[154:157], v[170:173], v[124:127]
	v_mfma_f32_16x16x32_bf16 v[120:123], v[162:165], v[170:173], v[120:123]
	v_mfma_f32_16x16x32_bf16 v[112:115], v[154:157], v[178:181], v[112:115]
	v_mfma_f32_16x16x32_bf16 v[104:107], v[162:165], v[178:181], v[104:107]
	v_mfma_f32_16x16x32_bf16 v[96:99], v[154:157], v[186:189], v[96:99]
	v_mfma_f32_16x16x32_bf16 v[88:91], v[162:165], v[186:189], v[88:91]
	v_mfma_f32_16x16x32_bf16 v[80:83], v[154:157], v[194:197], v[80:83]
	v_mfma_f32_16x16x32_bf16 v[72:75], v[162:165], v[194:197], v[72:75]
	v_mfma_f32_16x16x32_bf16 v[124:127], v[158:161], v[174:177], v[124:127]
	v_mfma_f32_16x16x32_bf16 v[120:123], v[166:169], v[174:177], v[120:123]
	v_mfma_f32_16x16x32_bf16 v[112:115], v[158:161], v[182:185], v[112:115]
	v_mfma_f32_16x16x32_bf16 v[104:107], v[166:169], v[182:185], v[104:107]
	v_mfma_f32_16x16x32_bf16 v[96:99], v[158:161], v[190:193], v[96:99]
	v_mfma_f32_16x16x32_bf16 v[88:91], v[166:169], v[190:193], v[88:91]
	v_mfma_f32_16x16x32_bf16 v[80:83], v[158:161], v[198:201], v[80:83]
	v_mfma_f32_16x16x32_bf16 v[72:75], v[166:169], v[198:201], v[72:75]
	s_setprio 0
	s_barrier
	s_add_i32 s22, 16, 0x1c000
	s_add_i32 s23, s53, s27
	v_add_u32_e32 v153, s22, v148
	s_mov_b32 m0, s23
	ds_read_b128 v[202:205], v153
	ds_read_b128 v[206:209], v153 offset:1024
	ds_read_b128 v[210:213], v153 offset:2048
	ds_read_b128 v[214:217], v153 offset:3072
	global_load_lds_dwordx4 v132, s[98:99]
	s_add_i32 m0, s23, 0x2000
	s_nop 0
	global_load_lds_dwordx4 v136, s[98:99]
	s_barrier
	s_waitcnt lgkmcnt(0)
	s_setprio 1
	s_waitcnt lgkmcnt(0)
	v_mfma_f32_16x16x32_bf16 v[116:119], v[202:205], v[170:173], v[116:119]
	v_mfma_f32_16x16x32_bf16 v[108:111], v[210:213], v[170:173], v[108:111]
	v_mfma_f32_16x16x32_bf16 v[100:103], v[202:205], v[178:181], v[100:103]
	v_mfma_f32_16x16x32_bf16 v[92:95], v[210:213], v[178:181], v[92:95]
	v_mfma_f32_16x16x32_bf16 v[84:87], v[202:205], v[186:189], v[84:87]
	v_mfma_f32_16x16x32_bf16 v[76:79], v[210:213], v[186:189], v[76:79]
	v_mfma_f32_16x16x32_bf16 v[68:71], v[202:205], v[194:197], v[68:71]
	v_mfma_f32_16x16x32_bf16 v[64:67], v[210:213], v[194:197], v[64:67]
	v_mfma_f32_16x16x32_bf16 v[116:119], v[206:209], v[174:177], v[116:119]
	v_mfma_f32_16x16x32_bf16 v[108:111], v[214:217], v[174:177], v[108:111]
	v_mfma_f32_16x16x32_bf16 v[100:103], v[206:209], v[182:185], v[100:103]
	v_mfma_f32_16x16x32_bf16 v[92:95], v[214:217], v[182:185], v[92:95]
	v_mfma_f32_16x16x32_bf16 v[84:87], v[206:209], v[190:193], v[84:87]
	v_mfma_f32_16x16x32_bf16 v[76:79], v[214:217], v[190:193], v[76:79]
	v_mfma_f32_16x16x32_bf16 v[68:71], v[206:209], v[198:201], v[68:71]
	v_mfma_f32_16x16x32_bf16 v[64:67], v[214:217], v[198:201], v[64:67]
	s_setprio 0
	s_mov_b32 m0, s37
	s_barrier
	ds_read_b128 v[170:173], v151 offset:49152
	ds_read_b128 v[174:177], v151 offset:50176
	ds_read_b128 v[178:181], v151 offset:51200
	ds_read_b128 v[182:185], v151 offset:52224
	ds_read_b128 v[186:189], v151 offset:53248
	ds_read_b128 v[190:193], v151 offset:54272
	ds_read_b128 v[194:197], v151 offset:55296
	ds_read_b128 v[198:201], v151 offset:56320
	global_load_lds_dwordx4 v130, s[100:101]
	s_mov_b32 m0, s38
	s_nop 0
	global_load_lds_dwordx4 v134, s[100:101]
	s_barrier
	s_waitcnt lgkmcnt(0)
	s_setprio 1
	s_waitcnt lgkmcnt(0)
	v_mfma_f32_16x16x32_bf16 v[60:63], v[154:157], v[170:173], v[60:63]
	v_mfma_f32_16x16x32_bf16 v[56:59], v[162:165], v[170:173], v[56:59]
	v_mfma_f32_16x16x32_bf16 v[48:51], v[154:157], v[178:181], v[48:51]
	v_mfma_f32_16x16x32_bf16 v[40:43], v[162:165], v[178:181], v[40:43]
	v_mfma_f32_16x16x32_bf16 v[32:35], v[154:157], v[186:189], v[32:35]
	v_mfma_f32_16x16x32_bf16 v[24:27], v[162:165], v[186:189], v[24:27]
	v_mfma_f32_16x16x32_bf16 v[16:19], v[154:157], v[194:197], v[16:19]
	v_mfma_f32_16x16x32_bf16 v[8:11], v[162:165], v[194:197], v[8:11]
	v_mfma_f32_16x16x32_bf16 v[60:63], v[158:161], v[174:177], v[60:63]
	v_mfma_f32_16x16x32_bf16 v[56:59], v[166:169], v[174:177], v[56:59]
	v_mfma_f32_16x16x32_bf16 v[48:51], v[158:161], v[182:185], v[48:51]
	v_mfma_f32_16x16x32_bf16 v[40:43], v[166:169], v[182:185], v[40:43]
	v_mfma_f32_16x16x32_bf16 v[32:35], v[158:161], v[190:193], v[32:35]
	v_mfma_f32_16x16x32_bf16 v[24:27], v[166:169], v[190:193], v[24:27]
	v_mfma_f32_16x16x32_bf16 v[16:19], v[158:161], v[198:201], v[16:19]
	v_mfma_f32_16x16x32_bf16 v[8:11], v[166:169], v[198:201], v[8:11]
	s_setprio 0
	s_barrier
	s_add_u32 s20, s20, 0x80080
	s_addc_u32 s21, s21, 0
	s_add_i32 s22, s22, s27
	s_mov_b32 m0, s22
	s_nop 0
	global_load_lds_dwordx4 v132, s[20:21]
	s_add_i32 m0, s22, 0x2000
	s_nop 0
	global_load_lds_dwordx4 v136, s[20:21]
	s_waitcnt vmcnt(6)
	s_barrier
	s_setprio 1
	v_mfma_f32_16x16x32_bf16 v[52:55], v[202:205], v[170:173], v[52:55]
	v_mfma_f32_16x16x32_bf16 v[44:47], v[210:213], v[170:173], v[44:47]
	v_mfma_f32_16x16x32_bf16 v[36:39], v[202:205], v[178:181], v[36:39]
	v_mfma_f32_16x16x32_bf16 v[28:31], v[210:213], v[178:181], v[28:31]
	v_mfma_f32_16x16x32_bf16 v[20:23], v[202:205], v[186:189], v[20:23]
	v_mfma_f32_16x16x32_bf16 v[12:15], v[210:213], v[186:189], v[12:15]
	v_mfma_f32_16x16x32_bf16 v[4:7], v[202:205], v[194:197], v[4:7]
	v_mfma_f32_16x16x32_bf16 v[0:3], v[210:213], v[194:197], v[0:3]
	v_mfma_f32_16x16x32_bf16 v[52:55], v[206:209], v[174:177], v[52:55]
	v_mfma_f32_16x16x32_bf16 v[44:47], v[214:217], v[174:177], v[44:47]
	v_mfma_f32_16x16x32_bf16 v[36:39], v[206:209], v[182:185], v[36:39]
	v_mfma_f32_16x16x32_bf16 v[28:31], v[214:217], v[182:185], v[28:31]
	v_mfma_f32_16x16x32_bf16 v[20:23], v[206:209], v[190:193], v[20:23]
	v_mfma_f32_16x16x32_bf16 v[12:15], v[214:217], v[190:193], v[12:15]
	v_mfma_f32_16x16x32_bf16 v[4:7], v[206:209], v[198:201], v[4:7]
	v_mfma_f32_16x16x32_bf16 v[0:3], v[214:217], v[198:201], v[0:3]
	s_setprio 0
	s_add_i32 s52, s52, 2
	s_add_u32 s18, s18, 0x100
	s_addc_u32 s19, s19, 0
	s_add_u32 s50, s50, 0x100
	s_addc_u32 s51, s51, 0
	s_cmp_gt_u32 s52, 29
	s_barrier
	s_cbranch_scc0 .LBB0_187
	v_lshl_or_b32 v146, s43, 8, v149
	v_ashrrev_i32_e32 v147, 31, v146
	v_lshl_add_u32 v153, s16, 8, v129
	v_lshl_add_u64 v[146:147], v[146:147], 1, s[4:5]
	v_mad_i64_i32 v[154:155], s[18:19], v153, s42, v[146:147]
	v_pk_add_f32 v[126:127], v[126:127], 0 op_sel_hi:[1,0]
	v_pk_add_f32 v[124:125], v[124:125], 0 op_sel_hi:[1,0]
	v_pk_add_f32 v[156:157], v[122:123], 0 op_sel_hi:[1,0]
	v_pk_add_f32 v[122:123], v[120:121], 0 op_sel_hi:[1,0]
	v_cvt_pk_bf16_f32 v120, v124, v125
	v_cvt_pk_bf16_f32 v121, v126, v127
	v_pk_add_f32 v[116:117], v[116:117], 0 op_sel_hi:[1,0]
	v_cvt_pk_bf16_f32 v122, v122, v123
	v_cvt_pk_bf16_f32 v123, v156, v157
	global_store_dwordx4 v[154:155], v[120:123], off
	v_pk_add_f32 v[118:119], v[118:119], 0 op_sel_hi:[1,0]
	v_pk_add_f32 v[112:113], v[112:113], 0 op_sel_hi:[1,0]
	v_pk_add_f32 v[120:121], v[110:111], 0 op_sel_hi:[1,0]
	v_pk_add_f32 v[110:111], v[108:109], 0 op_sel_hi:[1,0]
	v_cvt_pk_bf16_f32 v108, v116, v117
	v_cvt_pk_bf16_f32 v109, v118, v119
	v_pk_add_f32 v[100:101], v[100:101], 0 op_sel_hi:[1,0]
	v_cvt_pk_bf16_f32 v110, v110, v111
	v_cvt_pk_bf16_f32 v111, v120, v121
	global_store_dwordx4 v[154:155], v[108:111], off offset:256
	v_pk_add_f32 v[102:103], v[102:103], 0 op_sel_hi:[1,0]
	v_pk_add_f32 v[96:97], v[96:97], 0 op_sel_hi:[1,0]
	v_or_b32_e32 v108, 16, v153
	v_mad_i64_i32 v[108:109], s[18:19], v108, s42, v[146:147]
	v_pk_add_f32 v[110:111], v[114:115], 0 op_sel_hi:[1,0]
	v_pk_add_f32 v[114:115], v[106:107], 0 op_sel_hi:[1,0]
	v_pk_add_f32 v[106:107], v[104:105], 0 op_sel_hi:[1,0]
	v_cvt_pk_bf16_f32 v104, v112, v113
	v_cvt_pk_bf16_f32 v105, v110, v111
	v_pk_add_f32 v[84:85], v[84:85], 0 op_sel_hi:[1,0]
	v_cvt_pk_bf16_f32 v106, v106, v107
	v_cvt_pk_bf16_f32 v107, v114, v115
	global_store_dwordx4 v[108:109], v[104:107], off
	v_pk_add_f32 v[86:87], v[86:87], 0 op_sel_hi:[1,0]
	v_pk_add_f32 v[80:81], v[80:81], 0 op_sel_hi:[1,0]
	v_pk_add_f32 v[104:105], v[94:95], 0 op_sel_hi:[1,0]
	v_pk_add_f32 v[94:95], v[92:93], 0 op_sel_hi:[1,0]
	v_cvt_pk_bf16_f32 v92, v100, v101
	v_cvt_pk_bf16_f32 v93, v102, v103
	v_pk_add_f32 v[68:69], v[68:69], 0 op_sel_hi:[1,0]
	v_cvt_pk_bf16_f32 v94, v94, v95
	v_cvt_pk_bf16_f32 v95, v104, v105
	global_store_dwordx4 v[108:109], v[92:95], off offset:256
	v_pk_add_f32 v[70:71], v[70:71], 0 op_sel_hi:[1,0]
	v_pk_add_f32 v[62:63], v[62:63], 0 op_sel_hi:[1,0]
	v_or_b32_e32 v92, 32, v153
	v_mad_i64_i32 v[92:93], s[18:19], v92, s42, v[146:147]
	v_pk_add_f32 v[94:95], v[98:99], 0 op_sel_hi:[1,0]
	v_pk_add_f32 v[98:99], v[90:91], 0 op_sel_hi:[1,0]
	v_pk_add_f32 v[90:91], v[88:89], 0 op_sel_hi:[1,0]
	v_cvt_pk_bf16_f32 v88, v96, v97
	v_cvt_pk_bf16_f32 v89, v94, v95
	v_pk_add_f32 v[60:61], v[60:61], 0 op_sel_hi:[1,0]
	v_cvt_pk_bf16_f32 v90, v90, v91
	v_cvt_pk_bf16_f32 v91, v98, v99
	global_store_dwordx4 v[92:93], v[88:91], off
	v_pk_add_f32 v[52:53], v[52:53], 0 op_sel_hi:[1,0]
	v_pk_add_f32 v[54:55], v[54:55], 0 op_sel_hi:[1,0]
	v_pk_add_f32 v[88:89], v[78:79], 0 op_sel_hi:[1,0]
	v_pk_add_f32 v[78:79], v[76:77], 0 op_sel_hi:[1,0]
	v_cvt_pk_bf16_f32 v76, v84, v85
	v_cvt_pk_bf16_f32 v77, v86, v87
	v_pk_add_f32 v[48:49], v[48:49], 0 op_sel_hi:[1,0]
	v_cvt_pk_bf16_f32 v78, v78, v79
	v_cvt_pk_bf16_f32 v79, v88, v89
	global_store_dwordx4 v[92:93], v[76:79], off offset:256
	v_pk_add_f32 v[36:37], v[36:37], 0 op_sel_hi:[1,0]
	v_pk_add_f32 v[38:39], v[38:39], 0 op_sel_hi:[1,0]
	v_or_b32_e32 v76, 48, v153
	v_mad_i64_i32 v[76:77], s[18:19], v76, s42, v[146:147]
	v_pk_add_f32 v[78:79], v[82:83], 0 op_sel_hi:[1,0]
	v_pk_add_f32 v[82:83], v[74:75], 0 op_sel_hi:[1,0]
	v_pk_add_f32 v[74:75], v[72:73], 0 op_sel_hi:[1,0]
	v_cvt_pk_bf16_f32 v72, v80, v81
	v_cvt_pk_bf16_f32 v73, v78, v79
	v_pk_add_f32 v[32:33], v[32:33], 0 op_sel_hi:[1,0]
	v_cvt_pk_bf16_f32 v74, v74, v75
	v_cvt_pk_bf16_f32 v75, v82, v83
	global_store_dwordx4 v[76:77], v[72:75], off
	v_pk_add_f32 v[20:21], v[20:21], 0 op_sel_hi:[1,0]
	v_pk_add_f32 v[22:23], v[22:23], 0 op_sel_hi:[1,0]
	v_pk_add_f32 v[72:73], v[66:67], 0 op_sel_hi:[1,0]
	v_pk_add_f32 v[66:67], v[64:65], 0 op_sel_hi:[1,0]
	v_cvt_pk_bf16_f32 v64, v68, v69
	v_cvt_pk_bf16_f32 v65, v70, v71
	v_pk_add_f32 v[16:17], v[16:17], 0 op_sel_hi:[1,0]
	v_cvt_pk_bf16_f32 v66, v66, v67
	v_cvt_pk_bf16_f32 v67, v72, v73
	global_store_dwordx4 v[76:77], v[64:67], off offset:256
	s_and_b64 vcc, exec, s[2:3]
	s_mov_b32 s43, s8
	v_add_u32_e32 v64, 0x80, v153
	v_mad_i64_i32 v[64:65], s[18:19], v64, s42, v[146:147]
	v_pk_add_f32 v[66:67], v[58:59], 0 op_sel_hi:[1,0]
	v_pk_add_f32 v[58:59], v[56:57], 0 op_sel_hi:[1,0]
	v_cvt_pk_bf16_f32 v56, v60, v61
	v_cvt_pk_bf16_f32 v57, v62, v63
	s_mov_b32 s16, s10
	v_cvt_pk_bf16_f32 v58, v58, v59
	v_cvt_pk_bf16_f32 v59, v66, v67
	global_store_dwordx4 v[64:65], v[56:59], off
	s_mov_b64 s[20:21], s[14:15]
	v_pk_add_f32 v[6:7], v[6:7], 0 op_sel_hi:[1,0]
	v_pk_add_f32 v[56:57], v[46:47], 0 op_sel_hi:[1,0]
	v_pk_add_f32 v[46:47], v[44:45], 0 op_sel_hi:[1,0]
	v_cvt_pk_bf16_f32 v44, v52, v53
	v_cvt_pk_bf16_f32 v45, v54, v55
	v_pk_add_f32 v[4:5], v[4:5], 0 op_sel_hi:[1,0]
	v_cvt_pk_bf16_f32 v46, v46, v47
	v_cvt_pk_bf16_f32 v47, v56, v57
	global_store_dwordx4 v[64:65], v[44:47], off offset:256
	s_nop 1
	v_add_u32_e32 v44, 0x90, v153
	v_mad_i64_i32 v[44:45], s[18:19], v44, s42, v[146:147]
	v_pk_add_f32 v[46:47], v[50:51], 0 op_sel_hi:[1,0]
	v_pk_add_f32 v[50:51], v[42:43], 0 op_sel_hi:[1,0]
	v_pk_add_f32 v[42:43], v[40:41], 0 op_sel_hi:[1,0]
	v_cvt_pk_bf16_f32 v40, v48, v49
	v_cvt_pk_bf16_f32 v41, v46, v47
	s_nop 0
	v_cvt_pk_bf16_f32 v42, v42, v43
	v_cvt_pk_bf16_f32 v43, v50, v51
	global_store_dwordx4 v[44:45], v[40:43], off
	s_nop 1
	v_pk_add_f32 v[40:41], v[30:31], 0 op_sel_hi:[1,0]
	v_pk_add_f32 v[30:31], v[28:29], 0 op_sel_hi:[1,0]
	v_cvt_pk_bf16_f32 v28, v36, v37
	v_cvt_pk_bf16_f32 v29, v38, v39
	s_nop 0
	v_cvt_pk_bf16_f32 v30, v30, v31
	v_cvt_pk_bf16_f32 v31, v40, v41
	global_store_dwordx4 v[44:45], v[28:31], off offset:256
	s_nop 1
	v_add_u32_e32 v28, 0xa0, v153
	v_mad_i64_i32 v[28:29], s[18:19], v28, s42, v[146:147]
	v_pk_add_f32 v[30:31], v[34:35], 0 op_sel_hi:[1,0]
	v_pk_add_f32 v[34:35], v[26:27], 0 op_sel_hi:[1,0]
	v_pk_add_f32 v[26:27], v[24:25], 0 op_sel_hi:[1,0]
	v_cvt_pk_bf16_f32 v24, v32, v33
	v_cvt_pk_bf16_f32 v25, v30, v31
	s_nop 0
	v_cvt_pk_bf16_f32 v26, v26, v27
	v_cvt_pk_bf16_f32 v27, v34, v35
	global_store_dwordx4 v[28:29], v[24:27], off
	s_nop 1
	v_pk_add_f32 v[24:25], v[14:15], 0 op_sel_hi:[1,0]
	v_pk_add_f32 v[14:15], v[12:13], 0 op_sel_hi:[1,0]
	v_cvt_pk_bf16_f32 v12, v20, v21
	v_cvt_pk_bf16_f32 v13, v22, v23
	s_nop 0
	v_cvt_pk_bf16_f32 v14, v14, v15
	v_cvt_pk_bf16_f32 v15, v24, v25
	global_store_dwordx4 v[28:29], v[12:15], off offset:256
	s_nop 1
	v_add_u32_e32 v12, 0xb0, v153
	v_mad_i64_i32 v[12:13], s[18:19], v12, s42, v[146:147]
	v_pk_add_f32 v[14:15], v[18:19], 0 op_sel_hi:[1,0]
	v_pk_add_f32 v[18:19], v[10:11], 0 op_sel_hi:[1,0]
	v_pk_add_f32 v[10:11], v[8:9], 0 op_sel_hi:[1,0]
	v_cvt_pk_bf16_f32 v8, v16, v17
	v_cvt_pk_bf16_f32 v9, v14, v15
	s_mov_b64 s[18:19], s[12:13]
	v_cvt_pk_bf16_f32 v10, v10, v11
	v_cvt_pk_bf16_f32 v11, v18, v19
	global_store_dwordx4 v[12:13], v[8:11], off
	s_nop 1
	v_pk_add_f32 v[8:9], v[2:3], 0 op_sel_hi:[1,0]
	v_pk_add_f32 v[2:3], v[0:1], 0 op_sel_hi:[1,0]
	v_cvt_pk_bf16_f32 v0, v4, v5
	v_cvt_pk_bf16_f32 v1, v6, v7
	s_nop 0
	v_cvt_pk_bf16_f32 v2, v2, v3
	v_cvt_pk_bf16_f32 v3, v8, v9
	global_store_dwordx4 v[12:13], v[0:3], off offset:256
	s_cbranch_vccz .LBB0_184
	s_waitcnt vmcnt(0)
	s_cmpk_gt_u32 s24, 0xff
	s_cbranch_scc1 .LBB0_191
	s_barrier

.LBB0_676:
	ds_read_b128 v[154:157], v151
	ds_read_b128 v[158:161], v151 offset:1024
	ds_read_b128 v[162:165], v151 offset:2048
	ds_read_b128 v[166:169], v151 offset:3072
	s_add_u32 s28, s26, 0xfff80080
	s_addc_u32 s29, s27, -1
	s_cmp_eq_u32 s66, 28
	s_cselect_b32 s31, s19, s29
	s_cselect_b32 s30, s62, s28
	s_cselect_b32 s29, s17, s65
	s_cselect_b32 s28, s63, s64
	s_add_i32 m0, s25, 0xc000
	ds_read_b128 v[170:173], v152
	ds_read_b128 v[174:177], v152 offset:1024
	ds_read_b128 v[178:181], v152 offset:2048
	ds_read_b128 v[182:185], v152 offset:3072
	ds_read_b128 v[186:189], v152 offset:4096
	ds_read_b128 v[190:193], v152 offset:5120
	ds_read_b128 v[194:197], v152 offset:6144
	ds_read_b128 v[198:201], v152 offset:7168
	global_load_lds_dwordx4 v138, s[26:27]
	s_add_i32 m0, s25, 0xe000
	s_nop 0
	global_load_lds_dwordx4 v140, s[26:27]
	s_waitcnt lgkmcnt(8)
	s_barrier
	s_waitcnt lgkmcnt(0)
	s_setprio 1
	s_waitcnt lgkmcnt(0)
	v_mfma_f32_16x16x32_bf16 v[124:127], v[154:157], v[170:173], v[124:127]
	v_mfma_f32_16x16x32_bf16 v[120:123], v[162:165], v[170:173], v[120:123]
	v_mfma_f32_16x16x32_bf16 v[108:111], v[154:157], v[178:181], v[108:111]
	v_mfma_f32_16x16x32_bf16 v[104:107], v[162:165], v[178:181], v[104:107]
	v_mfma_f32_16x16x32_bf16 v[92:95], v[154:157], v[186:189], v[92:95]
	v_mfma_f32_16x16x32_bf16 v[88:91], v[162:165], v[186:189], v[88:91]
	v_mfma_f32_16x16x32_bf16 v[76:79], v[154:157], v[194:197], v[76:79]
	v_mfma_f32_16x16x32_bf16 v[72:75], v[162:165], v[194:197], v[72:75]
	v_mfma_f32_16x16x32_bf16 v[124:127], v[158:161], v[174:177], v[124:127]
	v_mfma_f32_16x16x32_bf16 v[120:123], v[166:169], v[174:177], v[120:123]
	v_mfma_f32_16x16x32_bf16 v[108:111], v[158:161], v[182:185], v[108:111]
	v_mfma_f32_16x16x32_bf16 v[104:107], v[166:169], v[182:185], v[104:107]
	v_mfma_f32_16x16x32_bf16 v[92:95], v[158:161], v[190:193], v[92:95]
	v_mfma_f32_16x16x32_bf16 v[88:91], v[166:169], v[190:193], v[88:91]
	v_mfma_f32_16x16x32_bf16 v[76:79], v[158:161], v[198:201], v[76:79]
	v_mfma_f32_16x16x32_bf16 v[72:75], v[166:169], v[198:201], v[72:75]
	s_setprio 0
	s_barrier
	s_add_i32 s67, s53, s39
	s_add_u32 s98, s28, s8
	s_addc_u32 s99, s29, s9
	s_mov_b32 m0, s67
	ds_read_b128 v[202:205], v153
	ds_read_b128 v[206:209], v153 offset:1024
	ds_read_b128 v[210:213], v153 offset:2048
	ds_read_b128 v[214:217], v153 offset:3072
	global_load_lds_dwordx4 v132, s[28:29]
	s_add_i32 m0, s67, 0x2000
	s_nop 0
	global_load_lds_dwordx4 v136, s[28:29]
	s_barrier
	s_waitcnt lgkmcnt(0)
	s_setprio 1
	s_waitcnt lgkmcnt(0)
	v_mfma_f32_16x16x32_bf16 v[116:119], v[202:205], v[170:173], v[116:119]
	v_mfma_f32_16x16x32_bf16 v[112:115], v[210:213], v[170:173], v[112:115]
	v_mfma_f32_16x16x32_bf16 v[100:103], v[202:205], v[178:181], v[100:103]
	v_mfma_f32_16x16x32_bf16 v[96:99], v[210:213], v[178:181], v[96:99]
	v_mfma_f32_16x16x32_bf16 v[84:87], v[202:205], v[186:189], v[84:87]
	v_mfma_f32_16x16x32_bf16 v[80:83], v[210:213], v[186:189], v[80:83]
	v_mfma_f32_16x16x32_bf16 v[68:71], v[202:205], v[194:197], v[68:71]
	v_mfma_f32_16x16x32_bf16 v[64:67], v[210:213], v[194:197], v[64:67]
	v_mfma_f32_16x16x32_bf16 v[116:119], v[206:209], v[174:177], v[116:119]
	v_mfma_f32_16x16x32_bf16 v[112:115], v[214:217], v[174:177], v[112:115]
	v_mfma_f32_16x16x32_bf16 v[100:103], v[206:209], v[182:185], v[100:103]
	v_mfma_f32_16x16x32_bf16 v[96:99], v[214:217], v[182:185], v[96:99]
	v_mfma_f32_16x16x32_bf16 v[84:87], v[206:209], v[190:193], v[84:87]
	v_mfma_f32_16x16x32_bf16 v[80:83], v[214:217], v[190:193], v[80:83]
	v_mfma_f32_16x16x32_bf16 v[68:71], v[206:209], v[198:201], v[68:71]
	v_mfma_f32_16x16x32_bf16 v[64:67], v[214:217], v[198:201], v[64:67]
	s_setprio 0
	s_mov_b32 m0, s25
	s_add_u32 s100, s30, s8
	s_addc_u32 s101, s31, s9
	s_barrier
	ds_read_b128 v[170:173], v152 offset:16384
	ds_read_b128 v[174:177], v152 offset:17408
	ds_read_b128 v[178:181], v152 offset:18432
	ds_read_b128 v[182:185], v152 offset:19456
	ds_read_b128 v[186:189], v152 offset:20480
	ds_read_b128 v[190:193], v152 offset:21504
	ds_read_b128 v[194:197], v152 offset:22528
	ds_read_b128 v[198:201], v152 offset:23552
	global_load_lds_dwordx4 v130, s[30:31]
	s_mov_b32 m0, s41
	s_nop 0
	global_load_lds_dwordx4 v134, s[30:31]
	s_barrier
	s_waitcnt lgkmcnt(0)
	s_setprio 1
	s_waitcnt lgkmcnt(0)
	v_mfma_f32_16x16x32_bf16 v[60:63], v[154:157], v[170:173], v[60:63]
	v_mfma_f32_16x16x32_bf16 v[56:59], v[162:165], v[170:173], v[56:59]
	v_mfma_f32_16x16x32_bf16 v[48:51], v[154:157], v[178:181], v[48:51]
	v_mfma_f32_16x16x32_bf16 v[40:43], v[162:165], v[178:181], v[40:43]
	v_mfma_f32_16x16x32_bf16 v[32:35], v[154:157], v[186:189], v[32:35]
	v_mfma_f32_16x16x32_bf16 v[24:27], v[162:165], v[186:189], v[24:27]
	v_mfma_f32_16x16x32_bf16 v[16:19], v[154:157], v[194:197], v[16:19]
	v_mfma_f32_16x16x32_bf16 v[8:11], v[162:165], v[194:197], v[8:11]
	v_mfma_f32_16x16x32_bf16 v[60:63], v[158:161], v[174:177], v[60:63]
	v_mfma_f32_16x16x32_bf16 v[56:59], v[166:169], v[174:177], v[56:59]
	v_mfma_f32_16x16x32_bf16 v[48:51], v[158:161], v[182:185], v[48:51]
	v_mfma_f32_16x16x32_bf16 v[40:43], v[166:169], v[182:185], v[40:43]
	v_mfma_f32_16x16x32_bf16 v[32:35], v[158:161], v[190:193], v[32:35]
	v_mfma_f32_16x16x32_bf16 v[24:27], v[166:169], v[190:193], v[24:27]
	v_mfma_f32_16x16x32_bf16 v[16:19], v[158:161], v[198:201], v[16:19]
	v_mfma_f32_16x16x32_bf16 v[8:11], v[166:169], v[198:201], v[8:11]
	s_setprio 0
	s_barrier
	s_add_u32 s68, s28, 0x80000
	s_addc_u32 s69, s29, 0
	s_add_i32 s67, s54, s39
	s_mov_b32 m0, s67
	s_nop 0
	global_load_lds_dwordx4 v132, s[68:69]
	s_add_i32 m0, s67, 0x2000
	s_nop 0
	global_load_lds_dwordx4 v136, s[68:69]
	s_waitcnt vmcnt(6)
	s_barrier
	s_setprio 1
	v_mfma_f32_16x16x32_bf16 v[52:55], v[202:205], v[170:173], v[52:55]
	v_mfma_f32_16x16x32_bf16 v[44:47], v[210:213], v[170:173], v[44:47]
	v_mfma_f32_16x16x32_bf16 v[36:39], v[202:205], v[178:181], v[36:39]
	v_mfma_f32_16x16x32_bf16 v[28:31], v[210:213], v[178:181], v[28:31]
	v_mfma_f32_16x16x32_bf16 v[20:23], v[202:205], v[186:189], v[20:23]
	v_mfma_f32_16x16x32_bf16 v[12:15], v[210:213], v[186:189], v[12:15]
	v_mfma_f32_16x16x32_bf16 v[4:7], v[202:205], v[194:197], v[4:7]
	v_mfma_f32_16x16x32_bf16 v[0:3], v[210:213], v[194:197], v[0:3]
	v_mfma_f32_16x16x32_bf16 v[52:55], v[206:209], v[174:177], v[52:55]
	v_mfma_f32_16x16x32_bf16 v[44:47], v[214:217], v[174:177], v[44:47]
	v_mfma_f32_16x16x32_bf16 v[36:39], v[206:209], v[182:185], v[36:39]
	v_mfma_f32_16x16x32_bf16 v[28:31], v[214:217], v[182:185], v[28:31]
	v_mfma_f32_16x16x32_bf16 v[20:23], v[206:209], v[190:193], v[20:23]
	v_mfma_f32_16x16x32_bf16 v[12:15], v[214:217], v[190:193], v[12:15]
	v_mfma_f32_16x16x32_bf16 v[4:7], v[206:209], v[198:201], v[4:7]
	v_mfma_f32_16x16x32_bf16 v[0:3], v[214:217], v[198:201], v[0:3]
	s_setprio 0
	s_add_i32 s67, 16, 0x18000
	v_add_u32_e32 v166, s67, v149
	s_barrier
	ds_read_b128 v[154:157], v166
	ds_read_b128 v[158:161], v166 offset:1024
	ds_read_b128 v[162:165], v166 offset:2048
	ds_read_b128 v[166:169], v166 offset:3072
	s_add_u32 s30, s30, 0x80000
	s_addc_u32 s31, s31, 0
	s_mov_b32 m0, s42
	ds_read_b128 v[170:173], v152 offset:32768
	ds_read_b128 v[174:177], v152 offset:33792
	ds_read_b128 v[178:181], v152 offset:34816
	ds_read_b128 v[182:185], v152 offset:35840
	ds_read_b128 v[186:189], v152 offset:36864
	ds_read_b128 v[190:193], v152 offset:37888
	ds_read_b128 v[194:197], v152 offset:38912
	ds_read_b128 v[198:201], v152 offset:39936
	global_load_lds_dwordx4 v130, s[30:31]
	s_mov_b32 m0, s43
	s_nop 0
	global_load_lds_dwordx4 v134, s[30:31]
	s_waitcnt lgkmcnt(8)
	s_barrier
	s_waitcnt lgkmcnt(0)
	s_setprio 1
	s_waitcnt lgkmcnt(0)
	v_mfma_f32_16x16x32_bf16 v[124:127], v[154:157], v[170:173], v[124:127]
	v_mfma_f32_16x16x32_bf16 v[120:123], v[162:165], v[170:173], v[120:123]
	v_mfma_f32_16x16x32_bf16 v[108:111], v[154:157], v[178:181], v[108:111]
	v_mfma_f32_16x16x32_bf16 v[104:107], v[162:165], v[178:181], v[104:107]
	v_mfma_f32_16x16x32_bf16 v[92:95], v[154:157], v[186:189], v[92:95]
	v_mfma_f32_16x16x32_bf16 v[88:91], v[162:165], v[186:189], v[88:91]
	v_mfma_f32_16x16x32_bf16 v[76:79], v[154:157], v[194:197], v[76:79]
	v_mfma_f32_16x16x32_bf16 v[72:75], v[162:165], v[194:197], v[72:75]
	v_mfma_f32_16x16x32_bf16 v[124:127], v[158:161], v[174:177], v[124:127]
	v_mfma_f32_16x16x32_bf16 v[120:123], v[166:169], v[174:177], v[120:123]
	v_mfma_f32_16x16x32_bf16 v[108:111], v[158:161], v[182:185], v[108:111]
	v_mfma_f32_16x16x32_bf16 v[104:107], v[166:169], v[182:185], v[104:107]
	v_mfma_f32_16x16x32_bf16 v[92:95], v[158:161], v[190:193], v[92:95]
	v_mfma_f32_16x16x32_bf16 v[88:91], v[166:169], v[190:193], v[88:91]
	v_mfma_f32_16x16x32_bf16 v[76:79], v[158:161], v[198:201], v[76:79]
	v_mfma_f32_16x16x32_bf16 v[72:75], v[166:169], v[198:201], v[72:75]
	s_setprio 0
	s_barrier
	s_add_i32 s30, 16, 0x1c000
	s_add_i32 s31, s67, s39
	v_add_u32_e32 v214, s30, v149
	s_mov_b32 m0, s31
	ds_read_b128 v[202:205], v214
	ds_read_b128 v[206:209], v214 offset:1024
	ds_read_b128 v[210:213], v214 offset:2048
	ds_read_b128 v[214:217], v214 offset:3072
	global_load_lds_dwordx4 v132, s[98:99]
	s_add_i32 m0, s31, 0x2000
	s_nop 0
	global_load_lds_dwordx4 v136, s[98:99]
	s_barrier
	s_waitcnt lgkmcnt(0)
	s_setprio 1
	s_waitcnt lgkmcnt(0)
	v_mfma_f32_16x16x32_bf16 v[116:119], v[202:205], v[170:173], v[116:119]
	v_mfma_f32_16x16x32_bf16 v[112:115], v[210:213], v[170:173], v[112:115]
	v_mfma_f32_16x16x32_bf16 v[100:103], v[202:205], v[178:181], v[100:103]
	v_mfma_f32_16x16x32_bf16 v[96:99], v[210:213], v[178:181], v[96:99]
	v_mfma_f32_16x16x32_bf16 v[84:87], v[202:205], v[186:189], v[84:87]
	v_mfma_f32_16x16x32_bf16 v[80:83], v[210:213], v[186:189], v[80:83]
	v_mfma_f32_16x16x32_bf16 v[68:71], v[202:205], v[194:197], v[68:71]
	v_mfma_f32_16x16x32_bf16 v[64:67], v[210:213], v[194:197], v[64:67]
	v_mfma_f32_16x16x32_bf16 v[116:119], v[206:209], v[174:177], v[116:119]
	v_mfma_f32_16x16x32_bf16 v[112:115], v[214:217], v[174:177], v[112:115]
	v_mfma_f32_16x16x32_bf16 v[100:103], v[206:209], v[182:185], v[100:103]
	v_mfma_f32_16x16x32_bf16 v[96:99], v[214:217], v[182:185], v[96:99]
	v_mfma_f32_16x16x32_bf16 v[84:87], v[206:209], v[190:193], v[84:87]
	v_mfma_f32_16x16x32_bf16 v[80:83], v[214:217], v[190:193], v[80:83]
	v_mfma_f32_16x16x32_bf16 v[68:71], v[206:209], v[198:201], v[68:71]
	v_mfma_f32_16x16x32_bf16 v[64:67], v[214:217], v[198:201], v[64:67]
	s_setprio 0
	s_mov_b32 m0, s50
	s_barrier
	ds_read_b128 v[170:173], v152 offset:49152
	ds_read_b128 v[174:177], v152 offset:50176
	ds_read_b128 v[178:181], v152 offset:51200
	ds_read_b128 v[182:185], v152 offset:52224
	ds_read_b128 v[186:189], v152 offset:53248
	ds_read_b128 v[190:193], v152 offset:54272
	ds_read_b128 v[194:197], v152 offset:55296
	ds_read_b128 v[198:201], v152 offset:56320
	global_load_lds_dwordx4 v130, s[100:101]
	s_mov_b32 m0, s51
	s_nop 0
	global_load_lds_dwordx4 v134, s[100:101]
	s_barrier
	s_waitcnt lgkmcnt(0)
	s_setprio 1
	s_waitcnt lgkmcnt(0)
	v_mfma_f32_16x16x32_bf16 v[60:63], v[154:157], v[170:173], v[60:63]
	v_mfma_f32_16x16x32_bf16 v[56:59], v[162:165], v[170:173], v[56:59]
	v_mfma_f32_16x16x32_bf16 v[48:51], v[154:157], v[178:181], v[48:51]
	v_mfma_f32_16x16x32_bf16 v[40:43], v[162:165], v[178:181], v[40:43]
	v_mfma_f32_16x16x32_bf16 v[32:35], v[154:157], v[186:189], v[32:35]
	v_mfma_f32_16x16x32_bf16 v[24:27], v[162:165], v[186:189], v[24:27]
	v_mfma_f32_16x16x32_bf16 v[16:19], v[154:157], v[194:197], v[16:19]
	v_mfma_f32_16x16x32_bf16 v[8:11], v[162:165], v[194:197], v[8:11]
	v_mfma_f32_16x16x32_bf16 v[60:63], v[158:161], v[174:177], v[60:63]
	v_mfma_f32_16x16x32_bf16 v[56:59], v[166:169], v[174:177], v[56:59]
	v_mfma_f32_16x16x32_bf16 v[48:51], v[158:161], v[182:185], v[48:51]
	v_mfma_f32_16x16x32_bf16 v[40:43], v[166:169], v[182:185], v[40:43]
	v_mfma_f32_16x16x32_bf16 v[32:35], v[158:161], v[190:193], v[32:35]
	v_mfma_f32_16x16x32_bf16 v[24:27], v[166:169], v[190:193], v[24:27]
	v_mfma_f32_16x16x32_bf16 v[16:19], v[158:161], v[198:201], v[16:19]
	v_mfma_f32_16x16x32_bf16 v[8:11], v[166:169], v[198:201], v[8:11]
	s_setprio 0
	s_barrier
	s_add_u32 s28, s28, 0x80080
	s_addc_u32 s29, s29, 0
	s_add_i32 s30, s30, s39
	s_mov_b32 m0, s30
	s_nop 0
	global_load_lds_dwordx4 v132, s[28:29]
	s_add_i32 m0, s30, 0x2000
	s_nop 0
	global_load_lds_dwordx4 v136, s[28:29]
	s_waitcnt vmcnt(6)
	s_barrier
	s_setprio 1
	v_mfma_f32_16x16x32_bf16 v[52:55], v[202:205], v[170:173], v[52:55]
	v_mfma_f32_16x16x32_bf16 v[44:47], v[210:213], v[170:173], v[44:47]
	v_mfma_f32_16x16x32_bf16 v[36:39], v[202:205], v[178:181], v[36:39]
	v_mfma_f32_16x16x32_bf16 v[28:31], v[210:213], v[178:181], v[28:31]
	v_mfma_f32_16x16x32_bf16 v[20:23], v[202:205], v[186:189], v[20:23]
	v_mfma_f32_16x16x32_bf16 v[12:15], v[210:213], v[186:189], v[12:15]
	v_mfma_f32_16x16x32_bf16 v[4:7], v[202:205], v[194:197], v[4:7]
	v_mfma_f32_16x16x32_bf16 v[0:3], v[210:213], v[194:197], v[0:3]
	v_mfma_f32_16x16x32_bf16 v[52:55], v[206:209], v[174:177], v[52:55]
	v_mfma_f32_16x16x32_bf16 v[44:47], v[214:217], v[174:177], v[44:47]
	v_mfma_f32_16x16x32_bf16 v[36:39], v[206:209], v[182:185], v[36:39]
	v_mfma_f32_16x16x32_bf16 v[28:31], v[214:217], v[182:185], v[28:31]
	v_mfma_f32_16x16x32_bf16 v[20:23], v[206:209], v[190:193], v[20:23]
	v_mfma_f32_16x16x32_bf16 v[12:15], v[214:217], v[190:193], v[12:15]
	v_mfma_f32_16x16x32_bf16 v[4:7], v[206:209], v[198:201], v[4:7]
	v_mfma_f32_16x16x32_bf16 v[0:3], v[214:217], v[198:201], v[0:3]
	s_setprio 0
	s_add_i32 s66, s66, 2
	s_add_u32 s26, s26, 0x100
	s_addc_u32 s27, s27, 0
	s_add_u32 s64, s64, 0x100
	s_addc_u32 s65, s65, 0
	s_cmp_gt_u32 s66, 29
	s_barrier
	s_cbranch_scc0 .LBB0_676
	v_lshl_add_u32 v154, s24, 8, v148
	v_lshl_or_b32 v146, s61, 8, v150
	v_ashrrev_i32_e32 v147, 31, v146
	v_ashrrev_i32_e32 v155, 31, v154
	v_lshl_add_u64 v[156:157], v[146:147], 1, s[6:7]
	v_lshlrev_b64 v[146:147], 12, v[154:155]
	v_lshl_add_u64 v[146:147], v[156:157], 0, v[146:147]
	v_pk_add_f32 v[126:127], v[126:127], 0 op_sel_hi:[1,0]
	v_pk_add_f32 v[124:125], v[124:125], 0 op_sel_hi:[1,0]
	v_pk_add_f32 v[158:159], v[122:123], 0 op_sel_hi:[1,0]
	v_pk_add_f32 v[122:123], v[120:121], 0 op_sel_hi:[1,0]
	v_cvt_pk_bf16_f32 v120, v124, v125
	v_cvt_pk_bf16_f32 v121, v126, v127
	v_pk_add_f32 v[116:117], v[116:117], 0 op_sel_hi:[1,0]
	v_cvt_pk_bf16_f32 v122, v122, v123
	v_cvt_pk_bf16_f32 v123, v158, v159
	global_store_dwordx4 v[146:147], v[120:123], off
	v_pk_add_f32 v[118:119], v[118:119], 0 op_sel_hi:[1,0]
	v_pk_add_f32 v[110:111], v[110:111], 0 op_sel_hi:[1,0]
	v_pk_add_f32 v[120:121], v[114:115], 0 op_sel_hi:[1,0]
	v_pk_add_f32 v[114:115], v[112:113], 0 op_sel_hi:[1,0]
	v_cvt_pk_bf16_f32 v112, v116, v117
	v_cvt_pk_bf16_f32 v113, v118, v119
	v_pk_add_f32 v[108:109], v[108:109], 0 op_sel_hi:[1,0]
	v_cvt_pk_bf16_f32 v114, v114, v115
	v_cvt_pk_bf16_f32 v115, v120, v121
	global_store_dwordx4 v[146:147], v[112:115], off offset:256
	v_pk_add_f32 v[100:101], v[100:101], 0 op_sel_hi:[1,0]
	v_pk_add_f32 v[102:103], v[102:103], 0 op_sel_hi:[1,0]
	v_or_b32_e32 v112, 16, v154
	v_ashrrev_i32_e32 v113, 31, v112
	v_lshlrev_b64 v[112:113], 12, v[112:113]
	v_lshl_add_u64 v[112:113], v[156:157], 0, v[112:113]
	v_pk_add_f32 v[114:115], v[106:107], 0 op_sel_hi:[1,0]
	v_pk_add_f32 v[106:107], v[104:105], 0 op_sel_hi:[1,0]
	v_cvt_pk_bf16_f32 v104, v108, v109
	v_cvt_pk_bf16_f32 v105, v110, v111
	v_pk_add_f32 v[94:95], v[94:95], 0 op_sel_hi:[1,0]
	v_cvt_pk_bf16_f32 v106, v106, v107
	v_cvt_pk_bf16_f32 v107, v114, v115
	global_store_dwordx4 v[112:113], v[104:107], off
	v_pk_add_f32 v[92:93], v[92:93], 0 op_sel_hi:[1,0]
	v_pk_add_f32 v[84:85], v[84:85], 0 op_sel_hi:[1,0]
	v_pk_add_f32 v[104:105], v[98:99], 0 op_sel_hi:[1,0]
	v_pk_add_f32 v[98:99], v[96:97], 0 op_sel_hi:[1,0]
	v_cvt_pk_bf16_f32 v96, v100, v101
	v_cvt_pk_bf16_f32 v97, v102, v103
	v_pk_add_f32 v[86:87], v[86:87], 0 op_sel_hi:[1,0]
	v_cvt_pk_bf16_f32 v98, v98, v99
	v_cvt_pk_bf16_f32 v99, v104, v105
	global_store_dwordx4 v[112:113], v[96:99], off offset:256
	v_pk_add_f32 v[78:79], v[78:79], 0 op_sel_hi:[1,0]
	v_pk_add_f32 v[76:77], v[76:77], 0 op_sel_hi:[1,0]
	v_or_b32_e32 v96, 32, v154
	v_ashrrev_i32_e32 v97, 31, v96
	v_lshlrev_b64 v[96:97], 12, v[96:97]
	v_lshl_add_u64 v[96:97], v[156:157], 0, v[96:97]
	v_pk_add_f32 v[98:99], v[90:91], 0 op_sel_hi:[1,0]
	v_pk_add_f32 v[90:91], v[88:89], 0 op_sel_hi:[1,0]
	v_cvt_pk_bf16_f32 v88, v92, v93
	v_cvt_pk_bf16_f32 v89, v94, v95
	v_pk_add_f32 v[70:71], v[70:71], 0 op_sel_hi:[1,0]
	v_cvt_pk_bf16_f32 v90, v90, v91
	v_cvt_pk_bf16_f32 v91, v98, v99
	global_store_dwordx4 v[96:97], v[88:91], off
	v_pk_add_f32 v[68:69], v[68:69], 0 op_sel_hi:[1,0]
	v_pk_add_f32 v[60:61], v[60:61], 0 op_sel_hi:[1,0]
	v_pk_add_f32 v[88:89], v[82:83], 0 op_sel_hi:[1,0]
	v_pk_add_f32 v[82:83], v[80:81], 0 op_sel_hi:[1,0]
	v_cvt_pk_bf16_f32 v80, v84, v85
	v_cvt_pk_bf16_f32 v81, v86, v87
	v_pk_add_f32 v[62:63], v[62:63], 0 op_sel_hi:[1,0]
	v_cvt_pk_bf16_f32 v82, v82, v83
	v_cvt_pk_bf16_f32 v83, v88, v89
	global_store_dwordx4 v[96:97], v[80:83], off offset:256
	v_pk_add_f32 v[54:55], v[54:55], 0 op_sel_hi:[1,0]
	v_pk_add_f32 v[52:53], v[52:53], 0 op_sel_hi:[1,0]
	v_or_b32_e32 v80, 48, v154
	v_ashrrev_i32_e32 v81, 31, v80
	v_lshlrev_b64 v[80:81], 12, v[80:81]
	v_lshl_add_u64 v[80:81], v[156:157], 0, v[80:81]
	v_pk_add_f32 v[82:83], v[74:75], 0 op_sel_hi:[1,0]
	v_pk_add_f32 v[74:75], v[72:73], 0 op_sel_hi:[1,0]
	v_cvt_pk_bf16_f32 v72, v76, v77
	v_cvt_pk_bf16_f32 v73, v78, v79
	v_pk_add_f32 v[48:49], v[48:49], 0 op_sel_hi:[1,0]
	v_cvt_pk_bf16_f32 v74, v74, v75
	v_cvt_pk_bf16_f32 v75, v82, v83
	global_store_dwordx4 v[80:81], v[72:75], off
	v_pk_add_f32 v[38:39], v[38:39], 0 op_sel_hi:[1,0]
	v_pk_add_f32 v[36:37], v[36:37], 0 op_sel_hi:[1,0]
	v_pk_add_f32 v[72:73], v[66:67], 0 op_sel_hi:[1,0]
	v_pk_add_f32 v[66:67], v[64:65], 0 op_sel_hi:[1,0]
	v_cvt_pk_bf16_f32 v64, v68, v69
	v_cvt_pk_bf16_f32 v65, v70, v71
	v_pk_add_f32 v[32:33], v[32:33], 0 op_sel_hi:[1,0]
	v_cvt_pk_bf16_f32 v66, v66, v67
	v_cvt_pk_bf16_f32 v67, v72, v73
	global_store_dwordx4 v[80:81], v[64:67], off offset:256
	v_pk_add_f32 v[22:23], v[22:23], 0 op_sel_hi:[1,0]
	v_pk_add_f32 v[20:21], v[20:21], 0 op_sel_hi:[1,0]
	v_pk_add_f32 v[66:67], v[58:59], 0 op_sel_hi:[1,0]
	v_pk_add_f32 v[58:59], v[56:57], 0 op_sel_hi:[1,0]
	v_cvt_pk_bf16_f32 v56, v60, v61
	v_add_co_u32_e32 v60, vcc, s55, v146
	v_cvt_pk_bf16_f32 v57, v62, v63
	v_cvt_pk_bf16_f32 v58, v58, v59
	v_cvt_pk_bf16_f32 v59, v66, v67
	v_lshl_add_u64 v[64:65], v[146:147], 0, s[4:5]
	s_nop 0
	v_addc_co_u32_e32 v61, vcc, 0, v147, vcc
	global_store_dwordx4 v[60:61], v[56:59], off
	v_pk_add_f32 v[16:17], v[16:17], 0 op_sel_hi:[1,0]
	s_mov_b32 s61, s16
	v_pk_add_f32 v[56:57], v[46:47], 0 op_sel_hi:[1,0]
	v_pk_add_f32 v[46:47], v[44:45], 0 op_sel_hi:[1,0]
	v_cvt_pk_bf16_f32 v44, v52, v53
	v_cvt_pk_bf16_f32 v45, v54, v55
	s_mov_b32 s24, s18
	v_cvt_pk_bf16_f32 v46, v46, v47
	v_cvt_pk_bf16_f32 v47, v56, v57
	global_store_dwordx4 v[64:65], v[44:47], off offset:256
	s_mov_b64 s[28:29], s[22:23]
	s_mov_b64 s[26:27], s[20:21]
	v_pk_add_f32 v[46:47], v[50:51], 0 op_sel_hi:[1,0]
	v_pk_add_f32 v[50:51], v[42:43], 0 op_sel_hi:[1,0]
	v_pk_add_f32 v[42:43], v[40:41], 0 op_sel_hi:[1,0]
	v_cvt_pk_bf16_f32 v40, v48, v49
	v_cvt_pk_bf16_f32 v41, v46, v47
	v_add_co_u32_e32 v46, vcc, s56, v146
	v_cvt_pk_bf16_f32 v42, v42, v43
	v_cvt_pk_bf16_f32 v43, v50, v51
	v_lshl_add_u64 v[44:45], v[146:147], 0, s[10:11]
	s_nop 0
	v_addc_co_u32_e32 v47, vcc, 0, v147, vcc
	global_store_dwordx4 v[46:47], v[40:43], off
	v_pk_add_f32 v[6:7], v[6:7], 0 op_sel_hi:[1,0]
	v_pk_add_f32 v[4:5], v[4:5], 0 op_sel_hi:[1,0]
	v_pk_add_f32 v[40:41], v[30:31], 0 op_sel_hi:[1,0]
	v_pk_add_f32 v[30:31], v[28:29], 0 op_sel_hi:[1,0]
	v_cvt_pk_bf16_f32 v28, v36, v37
	v_cvt_pk_bf16_f32 v29, v38, v39
	s_nop 0
	v_cvt_pk_bf16_f32 v30, v30, v31
	v_cvt_pk_bf16_f32 v31, v40, v41
	global_store_dwordx4 v[44:45], v[28:31], off offset:256
	s_nop 1
	v_pk_add_f32 v[30:31], v[34:35], 0 op_sel_hi:[1,0]
	v_pk_add_f32 v[34:35], v[26:27], 0 op_sel_hi:[1,0]
	v_pk_add_f32 v[26:27], v[24:25], 0 op_sel_hi:[1,0]
	v_cvt_pk_bf16_f32 v24, v32, v33
	v_cvt_pk_bf16_f32 v25, v30, v31
	v_add_co_u32_e32 v30, vcc, s57, v146
	v_cvt_pk_bf16_f32 v26, v26, v27
	v_cvt_pk_bf16_f32 v27, v34, v35
	v_lshl_add_u64 v[28:29], v[146:147], 0, s[12:13]
	s_nop 0
	v_addc_co_u32_e32 v31, vcc, 0, v147, vcc
	global_store_dwordx4 v[30:31], v[24:27], off
	s_nop 1
	v_pk_add_f32 v[24:25], v[14:15], 0 op_sel_hi:[1,0]
	v_pk_add_f32 v[14:15], v[12:13], 0 op_sel_hi:[1,0]
	v_cvt_pk_bf16_f32 v12, v20, v21
	v_cvt_pk_bf16_f32 v13, v22, v23
	s_nop 0
	v_cvt_pk_bf16_f32 v14, v14, v15
	v_cvt_pk_bf16_f32 v15, v24, v25
	global_store_dwordx4 v[28:29], v[12:15], off offset:256
	s_nop 1
	v_pk_add_f32 v[14:15], v[18:19], 0 op_sel_hi:[1,0]
	v_pk_add_f32 v[18:19], v[10:11], 0 op_sel_hi:[1,0]
	v_pk_add_f32 v[10:11], v[8:9], 0 op_sel_hi:[1,0]
	v_cvt_pk_bf16_f32 v8, v16, v17
	v_cvt_pk_bf16_f32 v9, v14, v15
	v_add_co_u32_e32 v14, vcc, s60, v146
	v_lshl_add_u64 v[12:13], v[146:147], 0, s[14:15]
	s_nop 0
	v_addc_co_u32_e32 v15, vcc, 0, v147, vcc
	v_cvt_pk_bf16_f32 v10, v10, v11
	v_cvt_pk_bf16_f32 v11, v18, v19
	global_store_dwordx4 v[14:15], v[8:11], off
	s_and_b64 vcc, exec, s[2:3]
	s_nop 0
	v_pk_add_f32 v[8:9], v[2:3], 0 op_sel_hi:[1,0]
	v_pk_add_f32 v[2:3], v[0:1], 0 op_sel_hi:[1,0]
	v_cvt_pk_bf16_f32 v0, v4, v5
	v_cvt_pk_bf16_f32 v1, v6, v7
	s_nop 0
	v_cvt_pk_bf16_f32 v2, v2, v3
	v_cvt_pk_bf16_f32 v3, v8, v9
	global_store_dwordx4 v[12:13], v[0:3], off offset:256
	s_cbranch_vccz .LBB0_669
	s_waitcnt vmcnt(0)
	s_cmpk_gt_u32 s34, 0xff
	s_cbranch_scc1 .LBB0_680
	s_barrier
